# mamba2 final-norm loop and sgu rstd loop: loads hoisted/batched (on top of epilogue + rstd_prologue changes)
# speedup vs baseline: 1.0210x; 1.0028x over previous
; __device__ __forceinline__ void unpack8(u32x4 v, float* f) { f[0] = lo16(v.x); f[1] = hi16(v.x); f[2] = lo16(v.y); f[3] = hi16(v.y); f[4] = lo16(v.z); f[5] = hi16(v.z); f[6] = lo16(v.w); f[7] = hi16(v.w); }
; __device__ __forceinline__ void sgu_item(const Params& p, int l, int item, lptr lds) {
;     ...
;     for (int rr = 0; rr < 16; ++rr) { const int t = wave * 16 + rr; float f[8]; unpack8(*(const u32x4*)(proj + (tok0 + t) * PLD + C_V + lane * 8), f); float ss = 0.f;
; #pragma unroll
;         for (int e = 0; e < 8; ++e) ss += f[e] * f[e];
;         ss = wave_sum(ss); if (lane == 0) rstd[t] = rsqrtf(ss * (1.f / 512.f) + EPS); }
.LBB0_1494:
	s_waitcnt lgkmcnt(0)
	v_lshl_add_u64 v[4:5], v[2:3], 0, s[24:25]
	v_add_co_u32_e32 v88, vcc, 0x6000000, v4
	s_nop 1
	v_addc_co_u32_e32 v89, vcc, 0, v5, vcc
	global_load_dwordx4 v[88:91], v[88:89], off offset:1024
	v_add_co_u32_e32 v92, vcc, 0x6002000, v4
	s_nop 1
	v_addc_co_u32_e32 v93, vcc, 0, v5, vcc
	global_load_dwordx4 v[92:95], v[92:93], off offset:2624
	v_add_co_u32_e32 v96, vcc, 0x6005000, v4
	s_nop 1
	v_addc_co_u32_e32 v97, vcc, 0, v5, vcc
	global_load_dwordx4 v[96:99], v[96:97], off offset:128
	v_add_co_u32_e32 v100, vcc, 0x6007000, v4
	s_nop 1
	v_addc_co_u32_e32 v101, vcc, 0, v5, vcc
	global_load_dwordx4 v[100:103], v[100:101], off offset:1728
	v_add_co_u32_e32 v104, vcc, 0x6009000, v4
	s_nop 1
	v_addc_co_u32_e32 v105, vcc, 0, v5, vcc
	global_load_dwordx4 v[104:107], v[104:105], off offset:3328
	v_add_co_u32_e32 v108, vcc, 0x600c000, v4
	s_nop 1
	v_addc_co_u32_e32 v109, vcc, 0, v5, vcc
	global_load_dwordx4 v[108:111], v[108:109], off offset:832
	v_add_co_u32_e32 v112, vcc, 0x600e000, v4
	s_nop 1
	v_addc_co_u32_e32 v113, vcc, 0, v5, vcc
	global_load_dwordx4 v[112:115], v[112:113], off offset:2432
	v_add_co_u32_e32 v116, vcc, 0x6010000, v4
	s_nop 1
	v_addc_co_u32_e32 v117, vcc, 0, v5, vcc
	global_load_dwordx4 v[116:119], v[116:117], off offset:4032
	s_waitcnt vmcnt(7)
	v_lshlrev_b32_e32 v0, 16, v88
	v_and_b32_e32 v88, 0xffff0000, v88
	v_mul_f32_e32 v88, v88, v88
	v_lshlrev_b32_e32 v18, 16, v89
	v_fmac_f32_e32 v88, v0, v0
	v_and_b32_e32 v89, 0xffff0000, v89
	v_fmac_f32_e32 v88, v18, v18
	v_lshlrev_b32_e32 v19, 16, v90
	v_fmac_f32_e32 v88, v89, v89
	v_and_b32_e32 v90, 0xffff0000, v90
	v_fmac_f32_e32 v88, v19, v19
	v_lshlrev_b32_e32 v20, 16, v91
	v_fmac_f32_e32 v88, v90, v90
	v_and_b32_e32 v91, 0xffff0000, v91
	v_fmac_f32_e32 v88, v20, v20
	v_fmac_f32_e32 v88, v91, v91
	ds_bpermute_b32 v0, v8, v88
	s_waitcnt lgkmcnt(0)
	v_add_f32_e32 v0, v88, v0
	ds_bpermute_b32 v88, v9, v0
	s_waitcnt lgkmcnt(0)
	v_add_f32_e32 v0, v0, v88
	ds_bpermute_b32 v88, v10, v0
	s_waitcnt lgkmcnt(0)
	v_add_f32_e32 v0, v0, v88
	ds_bpermute_b32 v88, v11, v0
	s_waitcnt lgkmcnt(0)
	v_add_f32_e32 v0, v0, v88
	ds_bpermute_b32 v88, v12, v0
	s_waitcnt lgkmcnt(0)
	v_add_f32_e32 v0, v0, v88
	ds_bpermute_b32 v88, v13, v0
	s_and_saveexec_b64 s[26:27], s[2:3]
	s_cbranch_execz .LBB0_1496
	s_waitcnt lgkmcnt(0)
	v_add_f32_e32 v0, v0, v88
	v_fmamk_f32 v0, v0, 0x3b000000, v218
	v_mul_f32_e32 v88, 0x4b800000, v0
	v_cmp_gt_f32_e32 vcc, s40, v0
	s_nop 1
	v_cndmask_b32_e32 v0, v0, v88, vcc
	v_rsq_f32_e32 v0, v0
	s_nop 0
	v_mul_f32_e32 v88, 0x45800000, v0
	v_cndmask_b32_e32 v0, v0, v88, vcc
	v_mov_b32_e32 v88, s37
	ds_write_b32 v88, v0
.LBB0_1496:
	s_or_b64 exec, exec, s[26:27]
	s_waitcnt lgkmcnt(0)
	s_waitcnt vmcnt(6)
	v_lshlrev_b32_e32 v0, 16, v92
	v_and_b32_e32 v92, 0xffff0000, v92
	v_mul_f32_e32 v92, v92, v92
	v_lshlrev_b32_e32 v18, 16, v93
	v_fmac_f32_e32 v92, v0, v0
	v_and_b32_e32 v93, 0xffff0000, v93
	v_fmac_f32_e32 v92, v18, v18
	v_lshlrev_b32_e32 v19, 16, v94
	v_fmac_f32_e32 v92, v93, v93
	v_and_b32_e32 v94, 0xffff0000, v94
	v_fmac_f32_e32 v92, v19, v19
	v_lshlrev_b32_e32 v20, 16, v95
	v_fmac_f32_e32 v92, v94, v94
	v_and_b32_e32 v95, 0xffff0000, v95
	v_fmac_f32_e32 v92, v20, v20
	v_fmac_f32_e32 v92, v95, v95
	ds_bpermute_b32 v0, v8, v92
	s_waitcnt lgkmcnt(0)
	v_add_f32_e32 v0, v92, v0
	ds_bpermute_b32 v92, v9, v0
	s_waitcnt lgkmcnt(0)
	v_add_f32_e32 v0, v0, v92
	ds_bpermute_b32 v92, v10, v0
	s_waitcnt lgkmcnt(0)
	v_add_f32_e32 v0, v0, v92
	ds_bpermute_b32 v92, v11, v0
	s_waitcnt lgkmcnt(0)
	v_add_f32_e32 v0, v0, v92
	ds_bpermute_b32 v92, v12, v0
	s_waitcnt lgkmcnt(0)
	v_add_f32_e32 v0, v0, v92
	ds_bpermute_b32 v92, v13, v0
	s_and_saveexec_b64 s[26:27], s[2:3]
	s_cbranch_execz .LBB0_1498
	s_waitcnt lgkmcnt(0)
	v_add_f32_e32 v0, v0, v92
	v_fmamk_f32 v0, v0, 0x3b000000, v218
	v_mul_f32_e32 v92, 0x4b800000, v0
	v_cmp_gt_f32_e32 vcc, s40, v0
	s_nop 1
	v_cndmask_b32_e32 v0, v0, v92, vcc
	v_rsq_f32_e32 v0, v0
	s_nop 0
	v_mul_f32_e32 v92, 0x45800000, v0
	v_cndmask_b32_e32 v0, v0, v92, vcc
	v_mov_b32_e32 v92, s37
	ds_write_b32 v92, v0 offset:4
.LBB0_1498:
	s_or_b64 exec, exec, s[26:27]
	s_waitcnt lgkmcnt(0)
	s_waitcnt vmcnt(5)
	v_lshlrev_b32_e32 v0, 16, v96
	v_and_b32_e32 v96, 0xffff0000, v96
	v_mul_f32_e32 v96, v96, v96
	v_lshlrev_b32_e32 v18, 16, v97
	v_fmac_f32_e32 v96, v0, v0
	v_and_b32_e32 v97, 0xffff0000, v97
	v_fmac_f32_e32 v96, v18, v18
	v_lshlrev_b32_e32 v19, 16, v98
	v_fmac_f32_e32 v96, v97, v97
	v_and_b32_e32 v98, 0xffff0000, v98
	v_fmac_f32_e32 v96, v19, v19
	v_lshlrev_b32_e32 v20, 16, v99
	v_fmac_f32_e32 v96, v98, v98
	v_and_b32_e32 v99, 0xffff0000, v99
	v_fmac_f32_e32 v96, v20, v20
	v_fmac_f32_e32 v96, v99, v99
	ds_bpermute_b32 v0, v8, v96
	s_waitcnt lgkmcnt(0)
	v_add_f32_e32 v0, v96, v0
	ds_bpermute_b32 v96, v9, v0
	s_waitcnt lgkmcnt(0)
	v_add_f32_e32 v0, v0, v96
	ds_bpermute_b32 v96, v10, v0
	s_waitcnt lgkmcnt(0)
	v_add_f32_e32 v0, v0, v96
	ds_bpermute_b32 v96, v11, v0
	s_waitcnt lgkmcnt(0)
	v_add_f32_e32 v0, v0, v96
	ds_bpermute_b32 v96, v12, v0
	s_waitcnt lgkmcnt(0)
	v_add_f32_e32 v0, v0, v96
	ds_bpermute_b32 v96, v13, v0
	s_and_saveexec_b64 s[26:27], s[2:3]
	s_cbranch_execz .LBB0_1500
	s_waitcnt lgkmcnt(0)
	v_add_f32_e32 v0, v0, v96
	v_fmamk_f32 v0, v0, 0x3b000000, v218
	v_mul_f32_e32 v96, 0x4b800000, v0
	v_cmp_gt_f32_e32 vcc, s40, v0
	s_nop 1
	v_cndmask_b32_e32 v0, v0, v96, vcc
	v_rsq_f32_e32 v0, v0
	s_nop 0
	v_mul_f32_e32 v96, 0x45800000, v0
	v_cndmask_b32_e32 v0, v0, v96, vcc
	v_mov_b32_e32 v96, s37
	ds_write_b32 v96, v0 offset:8
; __device__ __forceinline__ void unpack8(u32x4 v, float* f) { f[0] = lo16(v.x); f[1] = hi16(v.x); f[2] = lo16(v.y); f[3] = hi16(v.y); f[4] = lo16(v.z); f[5] = hi16(v.z); f[6] = lo16(v.w); f[7] = hi16(v.w); }
; __device__ __forceinline__ void sgu_item(const Params& p, int l, int item, lptr lds) {
;     ...
;     for (int rr = 0; rr < 16; ++rr) { const int t = wave * 16 + rr; float f[8]; unpack8(*(const u32x4*)(proj + (tok0 + t) * PLD + C_V + lane * 8), f); float ss = 0.f;
; #pragma unroll
;         for (int e = 0; e < 8; ++e) ss += f[e] * f[e];
;         ss = wave_sum(ss); if (lane == 0) rstd[t] = rsqrtf(ss * (1.f / 512.f) + EPS); }
.LBB0_1500:
	s_or_b64 exec, exec, s[26:27]
	s_waitcnt lgkmcnt(0)
	s_waitcnt vmcnt(4)
	v_lshlrev_b32_e32 v0, 16, v100
	v_and_b32_e32 v100, 0xffff0000, v100
	v_mul_f32_e32 v100, v100, v100
	v_lshlrev_b32_e32 v18, 16, v101
	v_fmac_f32_e32 v100, v0, v0
	v_and_b32_e32 v101, 0xffff0000, v101
	v_fmac_f32_e32 v100, v18, v18
	v_lshlrev_b32_e32 v19, 16, v102
	v_fmac_f32_e32 v100, v101, v101
	v_and_b32_e32 v102, 0xffff0000, v102
	v_fmac_f32_e32 v100, v19, v19
	v_lshlrev_b32_e32 v20, 16, v103
	v_fmac_f32_e32 v100, v102, v102
	v_and_b32_e32 v103, 0xffff0000, v103
	v_fmac_f32_e32 v100, v20, v20
	v_fmac_f32_e32 v100, v103, v103
	ds_bpermute_b32 v0, v8, v100
	s_waitcnt lgkmcnt(0)
	v_add_f32_e32 v0, v100, v0
	ds_bpermute_b32 v100, v9, v0
	s_waitcnt lgkmcnt(0)
	v_add_f32_e32 v0, v0, v100
	ds_bpermute_b32 v100, v10, v0
	s_waitcnt lgkmcnt(0)
	v_add_f32_e32 v0, v0, v100
	ds_bpermute_b32 v100, v11, v0
	s_waitcnt lgkmcnt(0)
	v_add_f32_e32 v0, v0, v100
	ds_bpermute_b32 v100, v12, v0
	s_waitcnt lgkmcnt(0)
	v_add_f32_e32 v0, v0, v100
	ds_bpermute_b32 v100, v13, v0
	s_and_saveexec_b64 s[26:27], s[2:3]
	s_cbranch_execz .LBB0_1502
	s_waitcnt lgkmcnt(0)
	v_add_f32_e32 v0, v0, v100
	v_fmamk_f32 v0, v0, 0x3b000000, v218
	v_mul_f32_e32 v100, 0x4b800000, v0
	v_cmp_gt_f32_e32 vcc, s40, v0
	s_nop 1
	v_cndmask_b32_e32 v0, v0, v100, vcc
	v_rsq_f32_e32 v0, v0
	s_nop 0
	v_mul_f32_e32 v100, 0x45800000, v0
	v_cndmask_b32_e32 v0, v0, v100, vcc
	v_mov_b32_e32 v100, s37
	ds_write_b32 v100, v0 offset:12
.LBB0_1502:
	s_or_b64 exec, exec, s[26:27]
	s_waitcnt lgkmcnt(0)
	s_waitcnt vmcnt(3)
	v_lshlrev_b32_e32 v0, 16, v104
	v_and_b32_e32 v104, 0xffff0000, v104
	v_mul_f32_e32 v104, v104, v104
	v_lshlrev_b32_e32 v18, 16, v105
	v_fmac_f32_e32 v104, v0, v0
	v_and_b32_e32 v105, 0xffff0000, v105
	v_fmac_f32_e32 v104, v18, v18
	v_lshlrev_b32_e32 v19, 16, v106
	v_fmac_f32_e32 v104, v105, v105
	v_and_b32_e32 v106, 0xffff0000, v106
	v_fmac_f32_e32 v104, v19, v19
	v_lshlrev_b32_e32 v20, 16, v107
	v_fmac_f32_e32 v104, v106, v106
	v_and_b32_e32 v107, 0xffff0000, v107
	v_fmac_f32_e32 v104, v20, v20
	v_fmac_f32_e32 v104, v107, v107
	ds_bpermute_b32 v0, v8, v104
	s_waitcnt lgkmcnt(0)
	v_add_f32_e32 v0, v104, v0
	ds_bpermute_b32 v104, v9, v0
	s_waitcnt lgkmcnt(0)
	v_add_f32_e32 v0, v0, v104
	ds_bpermute_b32 v104, v10, v0
	s_waitcnt lgkmcnt(0)
	v_add_f32_e32 v0, v0, v104
	ds_bpermute_b32 v104, v11, v0
	s_waitcnt lgkmcnt(0)
	v_add_f32_e32 v0, v0, v104
	ds_bpermute_b32 v104, v12, v0
	s_waitcnt lgkmcnt(0)
	v_add_f32_e32 v0, v0, v104
	ds_bpermute_b32 v104, v13, v0
	s_and_saveexec_b64 s[26:27], s[2:3]
	s_cbranch_execz .LBB0_1504
	s_waitcnt lgkmcnt(0)
	v_add_f32_e32 v0, v0, v104
	v_fmamk_f32 v0, v0, 0x3b000000, v218
	v_mul_f32_e32 v104, 0x4b800000, v0
	v_cmp_gt_f32_e32 vcc, s40, v0
	s_nop 1
	v_cndmask_b32_e32 v0, v0, v104, vcc
	v_rsq_f32_e32 v0, v0
	s_nop 0
	v_mul_f32_e32 v104, 0x45800000, v0
	v_cndmask_b32_e32 v0, v0, v104, vcc
	v_mov_b32_e32 v104, s37
	ds_write_b32 v104, v0 offset:16
; __device__ __forceinline__ void unpack8(u32x4 v, float* f) { f[0] = lo16(v.x); f[1] = hi16(v.x); f[2] = lo16(v.y); f[3] = hi16(v.y); f[4] = lo16(v.z); f[5] = hi16(v.z); f[6] = lo16(v.w); f[7] = hi16(v.w); }
; __device__ __forceinline__ void sgu_item(const Params& p, int l, int item, lptr lds) {
;     ...
;     for (int rr = 0; rr < 16; ++rr) { const int t = wave * 16 + rr; float f[8]; unpack8(*(const u32x4*)(proj + (tok0 + t) * PLD + C_V + lane * 8), f); float ss = 0.f;
; #pragma unroll
;         for (int e = 0; e < 8; ++e) ss += f[e] * f[e];
;         ss = wave_sum(ss); if (lane == 0) rstd[t] = rsqrtf(ss * (1.f / 512.f) + EPS); }
.LBB0_1504:
	s_or_b64 exec, exec, s[26:27]
	s_waitcnt lgkmcnt(0)
	s_waitcnt vmcnt(2)
	v_lshlrev_b32_e32 v0, 16, v108
	v_and_b32_e32 v108, 0xffff0000, v108
	v_mul_f32_e32 v108, v108, v108
	v_lshlrev_b32_e32 v18, 16, v109
	v_fmac_f32_e32 v108, v0, v0
	v_and_b32_e32 v109, 0xffff0000, v109
	v_fmac_f32_e32 v108, v18, v18
	v_lshlrev_b32_e32 v19, 16, v110
	v_fmac_f32_e32 v108, v109, v109
	v_and_b32_e32 v110, 0xffff0000, v110
	v_fmac_f32_e32 v108, v19, v19
	v_lshlrev_b32_e32 v20, 16, v111
	v_fmac_f32_e32 v108, v110, v110
	v_and_b32_e32 v111, 0xffff0000, v111
	v_fmac_f32_e32 v108, v20, v20
	v_fmac_f32_e32 v108, v111, v111
	ds_bpermute_b32 v0, v8, v108
	s_waitcnt lgkmcnt(0)
	v_add_f32_e32 v0, v108, v0
	ds_bpermute_b32 v108, v9, v0
	s_waitcnt lgkmcnt(0)
	v_add_f32_e32 v0, v0, v108
	ds_bpermute_b32 v108, v10, v0
	s_waitcnt lgkmcnt(0)
	v_add_f32_e32 v0, v0, v108
	ds_bpermute_b32 v108, v11, v0
	s_waitcnt lgkmcnt(0)
	v_add_f32_e32 v0, v0, v108
	ds_bpermute_b32 v108, v12, v0
	s_waitcnt lgkmcnt(0)
	v_add_f32_e32 v0, v0, v108
	ds_bpermute_b32 v108, v13, v0
	s_and_saveexec_b64 s[26:27], s[2:3]
	s_cbranch_execz .LBB0_1506
	s_waitcnt lgkmcnt(0)
	v_add_f32_e32 v0, v0, v108
	v_fmamk_f32 v0, v0, 0x3b000000, v218
	v_mul_f32_e32 v108, 0x4b800000, v0
	v_cmp_gt_f32_e32 vcc, s40, v0
	s_nop 1
	v_cndmask_b32_e32 v0, v0, v108, vcc
	v_rsq_f32_e32 v0, v0
	s_nop 0
	v_mul_f32_e32 v108, 0x45800000, v0
	v_cndmask_b32_e32 v0, v0, v108, vcc
	v_mov_b32_e32 v108, s37
	ds_write_b32 v108, v0 offset:20
.LBB0_1506:
	s_or_b64 exec, exec, s[26:27]
	s_waitcnt lgkmcnt(0)
	s_waitcnt vmcnt(1)
	v_lshlrev_b32_e32 v0, 16, v112
	v_and_b32_e32 v112, 0xffff0000, v112
	v_mul_f32_e32 v112, v112, v112
	v_lshlrev_b32_e32 v18, 16, v113
	v_fmac_f32_e32 v112, v0, v0
	v_and_b32_e32 v113, 0xffff0000, v113
	v_fmac_f32_e32 v112, v18, v18
	v_lshlrev_b32_e32 v19, 16, v114
	v_fmac_f32_e32 v112, v113, v113
	v_and_b32_e32 v114, 0xffff0000, v114
	v_fmac_f32_e32 v112, v19, v19
	v_lshlrev_b32_e32 v20, 16, v115
	v_fmac_f32_e32 v112, v114, v114
	v_and_b32_e32 v115, 0xffff0000, v115
	v_fmac_f32_e32 v112, v20, v20
	v_fmac_f32_e32 v112, v115, v115
	ds_bpermute_b32 v0, v8, v112
	s_waitcnt lgkmcnt(0)
	v_add_f32_e32 v0, v112, v0
	ds_bpermute_b32 v112, v9, v0
	s_waitcnt lgkmcnt(0)
	v_add_f32_e32 v0, v0, v112
	ds_bpermute_b32 v112, v10, v0
	s_waitcnt lgkmcnt(0)
	v_add_f32_e32 v0, v0, v112
	ds_bpermute_b32 v112, v11, v0
	s_waitcnt lgkmcnt(0)
	v_add_f32_e32 v0, v0, v112
	ds_bpermute_b32 v112, v12, v0
	s_waitcnt lgkmcnt(0)
	v_add_f32_e32 v0, v0, v112
	ds_bpermute_b32 v112, v13, v0
	s_and_saveexec_b64 s[26:27], s[2:3]
	s_cbranch_execz .LBB0_1508
	s_waitcnt lgkmcnt(0)
	v_add_f32_e32 v0, v0, v112
	v_fmamk_f32 v0, v0, 0x3b000000, v218
	v_mul_f32_e32 v112, 0x4b800000, v0
	v_cmp_gt_f32_e32 vcc, s40, v0
	s_nop 1
	v_cndmask_b32_e32 v0, v0, v112, vcc
	v_rsq_f32_e32 v0, v0
	s_nop 0
	v_mul_f32_e32 v112, 0x45800000, v0
	v_cndmask_b32_e32 v0, v0, v112, vcc
	v_mov_b32_e32 v112, s37
	ds_write_b32 v112, v0 offset:24
.LBB0_1508:
	s_or_b64 exec, exec, s[26:27]
	s_waitcnt lgkmcnt(0)
	s_waitcnt vmcnt(0)
	v_and_b32_e32 v4, 0xffff0000, v116
	v_lshlrev_b32_e32 v0, 16, v116
	v_mul_f32_e32 v4, v4, v4
	v_lshlrev_b32_e32 v5, 16, v117
	v_fmac_f32_e32 v4, v0, v0
	v_and_b32_e32 v116, 0xffff0000, v117
	v_fmac_f32_e32 v4, v5, v5
	v_lshlrev_b32_e32 v117, 16, v118
	v_fmac_f32_e32 v4, v116, v116
	v_and_b32_e32 v118, 0xffff0000, v118
	v_fmac_f32_e32 v4, v117, v117
	v_lshlrev_b32_e32 v18, 16, v119
	v_fmac_f32_e32 v4, v118, v118
	v_and_b32_e32 v119, 0xffff0000, v119
	v_fmac_f32_e32 v4, v18, v18
	v_fmac_f32_e32 v4, v119, v119
	ds_bpermute_b32 v0, v8, v4
	s_waitcnt lgkmcnt(0)
	v_add_f32_e32 v0, v4, v0
	ds_bpermute_b32 v4, v9, v0
	s_waitcnt lgkmcnt(0)
	v_add_f32_e32 v0, v0, v4
	ds_bpermute_b32 v4, v10, v0
	s_waitcnt lgkmcnt(0)
	v_add_f32_e32 v0, v0, v4
	ds_bpermute_b32 v4, v11, v0
	s_waitcnt lgkmcnt(0)
	v_add_f32_e32 v0, v0, v4
	ds_bpermute_b32 v4, v12, v0
	s_waitcnt lgkmcnt(0)
	v_add_f32_e32 v0, v0, v4
	ds_bpermute_b32 v4, v13, v0
	s_and_saveexec_b64 s[26:27], s[2:3]
	s_cbranch_execz .LBB0_1493
	s_waitcnt lgkmcnt(0)
	v_add_f32_e32 v0, v0, v4
	v_fmamk_f32 v0, v0, 0x3b000000, v218
	v_mul_f32_e32 v4, 0x4b800000, v0
	v_cmp_gt_f32_e32 vcc, s40, v0
	s_nop 1
	v_cndmask_b32_e32 v0, v0, v4, vcc
	v_rsq_f32_e32 v0, v0
	s_nop 0
	v_mul_f32_e32 v4, 0x45800000, v0
	v_cndmask_b32_e32 v0, v0, v4, vcc
	v_mov_b32_e32 v4, s37
	ds_write_b32 v4, v0 offset:28
	s_branch .LBB0_1493

; __device__ __forceinline__ unsigned pk2(float lo, float hi) { const f32x2 v = {lo, hi}; const bf16x2_t b = __builtin_convertvector(v, bf16x2_t); return __builtin_bit_cast(unsigned, b); }
; __device__ __forceinline__ float lo16(unsigned w) { return __uint_as_float(w << 16); }
; __device__ __forceinline__ float hi16(unsigned w) { return __uint_as_float(w & 0xffff0000u); }
; __device__ __forceinline__ void mamba2_item(const Params& p, int l, int item, lptr lds) {
;     ...
;     for (int h = 0; h < 8; ++h)
; #pragma unroll
;         for (int pi = 0; pi < 4; ++pi) { const int col = h * 64 + pi * 16 + fq * 4; u32x2* ptr = (u32x2*)(ys + (tokbase + l_row) * YLD + 512 + col); const u32x2 r = *ptr; const f32x4 gg = *(const f32x4*)(ng + col);
;             u32x2 ov; ov.x = pk2(lo16(r.x) * rs * gg.x, hi16(r.x) * rs * gg.y); ov.y = pk2(lo16(r.y) * rs * gg.z, hi16(r.y) * rs * gg.w); *ptr = ov; }
;     __syncthreads();
.LBB0_1884:
	v_lshl_add_u64 v[8:9], v[4:5], 0, s[2:3]
	global_load_dwordx2 v[20:21], v[6:7], off offset:-64
	global_load_dwordx2 v[22:23], v[6:7], off offset:-32
	global_load_dwordx2 v[24:25], v[6:7], off
	global_load_dwordx2 v[26:27], v[6:7], off offset:32
	global_load_dwordx4 v[28:31], v[8:9], off
	global_load_dwordx4 v[32:35], v[8:9], off offset:64
	global_load_dwordx4 v[36:39], v[8:9], off offset:128
	global_load_dwordx4 v[40:43], v[8:9], off offset:192
	s_add_u32 s2, s2, 0x100
	s_addc_u32 s3, s3, 0
	s_cmpk_lg_i32 s2, 0x800
	s_waitcnt vmcnt(3)
	v_lshlrev_b32_e32 v44, 16, v20
	v_and_b32_e32 v45, 0xffff0000, v20
	v_lshlrev_b32_e32 v46, 16, v21
	v_and_b32_e32 v47, 0xffff0000, v21
	v_pk_mul_f32 v[44:45], v[2:3], v[44:45]
	v_pk_mul_f32 v[46:47], v[2:3], v[46:47]
	v_pk_mul_f32 v[48:49], v[28:29], v[44:45]
	v_pk_mul_f32 v[50:51], v[30:31], v[46:47]
	v_cvt_pk_bf16_f32 v48, v48, v49
	v_cvt_pk_bf16_f32 v49, v50, v51
	global_store_dwordx2 v[6:7], v[48:49], off offset:-64
	s_waitcnt vmcnt(3)
	v_lshlrev_b32_e32 v52, 16, v22
	v_and_b32_e32 v53, 0xffff0000, v22
	v_lshlrev_b32_e32 v54, 16, v23
	v_and_b32_e32 v55, 0xffff0000, v23
	v_pk_mul_f32 v[52:53], v[2:3], v[52:53]
	v_pk_mul_f32 v[54:55], v[2:3], v[54:55]
	v_pk_mul_f32 v[56:57], v[32:33], v[52:53]
	v_pk_mul_f32 v[58:59], v[34:35], v[54:55]
	v_cvt_pk_bf16_f32 v56, v56, v57
	v_cvt_pk_bf16_f32 v57, v58, v59
	global_store_dwordx2 v[6:7], v[56:57], off offset:-32
	s_waitcnt vmcnt(3)
	v_lshlrev_b32_e32 v60, 16, v24
	v_and_b32_e32 v61, 0xffff0000, v24
	v_lshlrev_b32_e32 v62, 16, v25
	v_and_b32_e32 v63, 0xffff0000, v25
	v_pk_mul_f32 v[60:61], v[2:3], v[60:61]
	v_pk_mul_f32 v[62:63], v[2:3], v[62:63]
	v_pk_mul_f32 v[64:65], v[36:37], v[60:61]
	v_pk_mul_f32 v[66:67], v[38:39], v[62:63]
	v_cvt_pk_bf16_f32 v64, v64, v65
	v_cvt_pk_bf16_f32 v65, v66, v67
	global_store_dwordx2 v[6:7], v[64:65], off
	s_waitcnt vmcnt(3)
	v_lshlrev_b32_e32 v68, 16, v26
	v_and_b32_e32 v69, 0xffff0000, v26
	v_lshlrev_b32_e32 v70, 16, v27
	v_and_b32_e32 v71, 0xffff0000, v27
	v_pk_mul_f32 v[68:69], v[2:3], v[68:69]
	v_pk_mul_f32 v[70:71], v[2:3], v[70:71]
	v_pk_mul_f32 v[72:73], v[40:41], v[68:69]
	v_pk_mul_f32 v[74:75], v[42:43], v[70:71]
	v_cvt_pk_bf16_f32 v72, v72, v73
	v_cvt_pk_bf16_f32 v73, v74, v75
	global_store_dwordx2 v[6:7], v[72:73], off offset:32
	v_lshl_add_u64 v[6:7], v[6:7], 0, s[6:7]
	s_cbranch_scc1 .LBB0_1884
	v_readlane_b32 s72, v253, 49
	v_readlane_b32 s68, v254, 1
	v_readlane_b32 s50, v254, 15
	v_readlane_b32 s73, v253, 50
	v_readlane_b32 s74, v253, 51
	v_readlane_b32 s75, v253, 52
	v_readlane_b32 s76, v253, 53
	v_readlane_b32 s77, v253, 54
	v_readlane_b32 s78, v253, 55
	v_readlane_b32 s79, v253, 56
	v_readlane_b32 s80, v253, 57
	v_readlane_b32 s81, v253, 58
	v_readlane_b32 s82, v253, 59
	v_readlane_b32 s83, v253, 60
	v_readlane_b32 s84, v253, 61
	v_readlane_b32 s85, v253, 62
	v_readlane_b32 s86, v253, 63
	v_readlane_b32 s87, v254, 0
	v_readlane_b32 s69, v254, 2
	s_movk_i32 s64, 0x100
	s_movk_i32 s70, 0x2640
	v_readlane_b32 s51, v254, 16
	s_barrier
	s_and_saveexec_b64 s[2:3], s[96:97]
	s_cbranch_execz .LBB0_1662
	s_branch .LBB0_1936
